# combo6 + small_gemm K loops: 24 fragment loads up front + 8 rolling with counted waits (6 copies)
# speedup vs baseline: 1.0218x; 1.0080x over previous
; __device__ __forceinline__ unsigned cvt_pk_bf16(float lo, float hi) { const f32v2_t v = {lo, hi}; const bf16v2_t r = __builtin_convertvector(v, bf16v2_t); return __builtin_bit_cast(unsigned, r); }
; __device__ __forceinline__ f32x4 mfma16(const bf16x8& a, const bf16x8& b, const f32x4& c) { return __builtin_amdgcn_mfma_f32_16x16x32_bf16(a, b, c, 0, 0, 0); }
;     __device__ __forceinline__ void operator()(int row, int col, const f32x4& acc) const {
;         if constexpr (NORM) { const f32x4 bv = *(const f32x4*)(base + (size_t)row * DM + col); const f32x4 v = acc + bv;
;             float ss = (v[0] * v[0] + v[1] * v[1]) + (v[2] * v[2] + v[3] * v[3]);
;             u32x2 w; w.x = cvt_pk_bf16(v[0], v[1]); w.y = cvt_pk_bf16(v[2], v[3]); *(u32x2*)(a3 + (size_t)row * DM + col) = w;
;             ss += __shfl_xor(ss, 16); ss += __shfl_xor(ss, 32); if ((threadIdx.x & 48) == 0) atomicAdd(rowss + row, ss);
; template <int KS, class Epi>
; __device__ __forceinline__ void small_gemm(const bf16_t* __restrict__ A, int lda, int a_grp_step, const bf16_t* __restrict__ Bt, int N, const Epi& E, LAS unsigned char* lds) {
;     ...
;         const int tile = pair * 2 + th, tr = tile & 15, tc = tile >> 4, row0 = MP + tr * 32, col0 = tc * 32;
;         const bf16_t* ap = A + (size_t)(row0 + fr) * lda + (col0 >> 8) * a_grp_step + kq * (KS * 32) + 8 * fq;
;         const bf16_t* bp = Bt + (size_t)(col0 + fr) * K + kq * (KS * 32) + 8 * fq;
;         bf16x8 a[KS][2], b[KS][2];
; #pragma unroll
;         for (int k = 0; k < KS; ++k)
; #pragma unroll
;             for (int m = 0; m < 2; ++m) { a[k][m] = *(const bf16x8*)(ap + (size_t)(16 * m) * lda + 32 * k); b[k][m] = *(const bf16x8*)(bp + (size_t)(16 * m) * K + 32 * k); }
;         f32x4 acc[2][2];
; #pragma unroll
;         for (int mi = 0; mi < 2; ++mi)
; #pragma unroll
;             for (int ni = 0; ni < 2; ++ni) acc[mi][ni] = (f32x4){0.f, 0.f, 0.f, 0.f};
; #pragma unroll
;         for (int k = 0; k < KS; ++k)
; #pragma unroll
;             for (int mi = 0; mi < 2; ++mi)
; #pragma unroll
;                 for (int ni = 0; ni < 2; ++ni) acc[mi][ni] = mfma16(b[k][ni], a[k][mi], acc[mi][ni]);
; #pragma unroll
;         for (int mi = 0; mi < 2; ++mi)
; #pragma unroll
;             for (int ni = 0; ni < 2; ++ni) red[(wid * 4 + mi * 2 + ni) * 64 + lane] = acc[mi][ni];
;         lds_barrier();
.LBB0_729:
	v_and_b32_e32 v70, 0xffffffe0, v9
	v_or_b32_e32 v18, v70, v146
	v_and_b32_e32 v0, 0x1e0, v10
	s_waitcnt lgkmcnt(0)
	v_ashrrev_i32_e32 v19, 31, v18
	v_or_b32_e32 v17, 0x4000, v0
	v_lshlrev_b64 v[18:19], 11, v[18:19]
	v_lshl_add_u64 v[62:63], v[4:5], 0, v[18:19]
	v_or_b32_e32 v0, v17, v146
	v_lshlrev_b32_e32 v0, 11, v0
	v_lshl_add_u64 v[64:65], v[2:3], 0, v[0:1]
	v_add_co_u32_e64 v66, s[2:3], s14, v64
	v_addc_co_u32_e64 v67, s[2:3], 0, v65, s[2:3]
	v_add_co_u32_e64 v68, s[2:3], s14, v62
	v_addc_co_u32_e64 v69, s[2:3], 0, v63, s[2:3]
	v_or_b32_e32 v17, v7, v17
	v_lshlrev_b32_e32 v0, 12, v17
	v_cmp_lt_i32_e64 s[2:3], v14, v15
	v_or_b32_e32 v38, v70, v8
	v_ashrrev_i32_e32 v39, 31, v38
	global_load_dwordx4 v[158:161], v[62:63], off
	global_load_dwordx4 v[162:165], v[64:65], off
	global_load_dwordx4 v[166:169], v[66:67], off
	global_load_dwordx4 v[170:173], v[68:69], off
	global_load_dwordx4 v[174:177], v[62:63], off offset:64
	global_load_dwordx4 v[178:181], v[64:65], off offset:64
	global_load_dwordx4 v[186:189], v[66:67], off offset:64
	global_load_dwordx4 v[190:193], v[68:69], off offset:64
	global_load_dwordx4 v[194:197], v[62:63], off offset:128
	global_load_dwordx4 v[198:201], v[64:65], off offset:128
	global_load_dwordx4 v[202:205], v[66:67], off offset:128
	global_load_dwordx4 v[206:209], v[68:69], off offset:128
	global_load_dwordx4 v[210:213], v[62:63], off offset:192
	global_load_dwordx4 v[214:217], v[64:65], off offset:192
	global_load_dwordx4 v[218:221], v[66:67], off offset:192
	global_load_dwordx4 v[222:225], v[68:69], off offset:192
	global_load_dwordx4 v[226:229], v[62:63], off offset:256
	global_load_dwordx4 v[230:233], v[64:65], off offset:256
	global_load_dwordx4 v[234:237], v[66:67], off offset:256
	global_load_dwordx4 v[238:241], v[68:69], off offset:256
	global_load_dwordx4 v[242:245], v[62:63], off offset:320
	global_load_dwordx4 v[118:121], v[64:65], off offset:320
	global_load_dwordx4 v[122:125], v[66:67], off offset:320
	global_load_dwordx4 v[148:151], v[68:69], off offset:320
	s_waitcnt vmcnt(20)
	v_mfma_f32_16x16x32_bf16 v[18:21], v[158:161], v[162:165], 0
	v_mfma_f32_16x16x32_bf16 v[22:25], v[158:161], v[166:169], 0
	v_mfma_f32_16x16x32_bf16 v[26:29], v[170:173], v[162:165], 0
	v_mfma_f32_16x16x32_bf16 v[30:33], v[170:173], v[166:169], 0
	global_load_dwordx4 v[158:161], v[62:63], off offset:384
	global_load_dwordx4 v[162:165], v[64:65], off offset:384
	global_load_dwordx4 v[166:169], v[66:67], off offset:384
	global_load_dwordx4 v[170:173], v[68:69], off offset:384
	s_waitcnt vmcnt(20)
	v_mfma_f32_16x16x32_bf16 v[18:21], v[174:177], v[178:181], v[18:21]
	v_mfma_f32_16x16x32_bf16 v[22:25], v[174:177], v[186:189], v[22:25]
	v_mfma_f32_16x16x32_bf16 v[26:29], v[190:193], v[178:181], v[26:29]
	v_mfma_f32_16x16x32_bf16 v[30:33], v[190:193], v[186:189], v[30:33]
	global_load_dwordx4 v[174:177], v[62:63], off offset:448
	global_load_dwordx4 v[178:181], v[64:65], off offset:448
	global_load_dwordx4 v[186:189], v[66:67], off offset:448
	global_load_dwordx4 v[190:193], v[68:69], off offset:448
	s_waitcnt vmcnt(20)
	v_mfma_f32_16x16x32_bf16 v[18:21], v[194:197], v[198:201], v[18:21]
	v_mfma_f32_16x16x32_bf16 v[22:25], v[194:197], v[202:205], v[22:25]
	v_mfma_f32_16x16x32_bf16 v[26:29], v[206:209], v[198:201], v[26:29]
	v_mfma_f32_16x16x32_bf16 v[30:33], v[206:209], v[202:205], v[30:33]
	s_waitcnt vmcnt(16)
	v_mfma_f32_16x16x32_bf16 v[18:21], v[210:213], v[214:217], v[18:21]
	v_mfma_f32_16x16x32_bf16 v[22:25], v[210:213], v[218:221], v[22:25]
	v_mfma_f32_16x16x32_bf16 v[26:29], v[222:225], v[214:217], v[26:29]
	v_mfma_f32_16x16x32_bf16 v[30:33], v[222:225], v[218:221], v[30:33]
	s_waitcnt vmcnt(12)
	v_mfma_f32_16x16x32_bf16 v[18:21], v[226:229], v[230:233], v[18:21]
	v_mfma_f32_16x16x32_bf16 v[22:25], v[226:229], v[234:237], v[22:25]
	v_mfma_f32_16x16x32_bf16 v[26:29], v[238:241], v[230:233], v[26:29]
	v_mfma_f32_16x16x32_bf16 v[30:33], v[238:241], v[234:237], v[30:33]
	s_waitcnt vmcnt(8)
	v_mfma_f32_16x16x32_bf16 v[18:21], v[242:245], v[118:121], v[18:21]
	v_mfma_f32_16x16x32_bf16 v[22:25], v[242:245], v[122:125], v[22:25]
	v_mfma_f32_16x16x32_bf16 v[26:29], v[148:151], v[118:121], v[26:29]
	v_mfma_f32_16x16x32_bf16 v[30:33], v[148:151], v[122:125], v[30:33]
	s_waitcnt vmcnt(4)
	v_mfma_f32_16x16x32_bf16 v[18:21], v[158:161], v[162:165], v[18:21]
	v_mfma_f32_16x16x32_bf16 v[22:25], v[158:161], v[166:169], v[22:25]
	v_mfma_f32_16x16x32_bf16 v[26:29], v[170:173], v[162:165], v[26:29]
	v_mfma_f32_16x16x32_bf16 v[30:33], v[170:173], v[166:169], v[30:33]
	s_waitcnt vmcnt(0)
	v_mfma_f32_16x16x32_bf16 v[18:21], v[174:177], v[178:181], v[18:21]
	v_mfma_f32_16x16x32_bf16 v[22:25], v[174:177], v[186:189], v[22:25]
	v_mfma_f32_16x16x32_bf16 v[26:29], v[190:193], v[178:181], v[26:29]
	v_mfma_f32_16x16x32_bf16 v[30:33], v[190:193], v[186:189], v[30:33]
	s_nop 7
	s_nop 3
	ds_write_b128 v11, v[18:21]
	ds_write_b128 v11, v[26:29] offset:1024
	ds_write_b128 v11, v[22:25] offset:2048
	ds_write_b128 v11, v[30:33] offset:3072
	v_lshl_add_u64 v[18:19], s[4:5], 0, v[0:1]
	s_waitcnt lgkmcnt(0)
	s_barrier
	v_lshl_add_u64 v[18:19], v[38:39], 2, v[18:19]
	global_load_dwordx4 v[18:21], v[18:19], off
	ds_read_b128 v[22:25], v6
	ds_read_b128 v[26:29], v12 offset:4096
	ds_read_b128 v[30:33], v12 offset:8192
	ds_read_b128 v[34:37], v12 offset:12288
	v_cndmask_b32_e64 v0, v13, v14, s[2:3]
	v_lshlrev_b32_e32 v0, 2, v0
	s_waitcnt lgkmcnt(0)
	v_pk_add_f32 v[24:25], v[24:25], v[28:29]
	v_pk_add_f32 v[22:23], v[22:23], v[26:27]
	v_pk_add_f32 v[24:25], v[24:25], v[32:33]
	v_pk_add_f32 v[22:23], v[22:23], v[30:31]
	v_pk_add_f32 v[24:25], v[24:25], v[36:37]
	v_pk_add_f32 v[22:23], v[22:23], v[34:35]
	v_cmp_lt_i32_e64 s[2:3], v16, v15
	s_waitcnt vmcnt(0)
	v_pk_add_f32 v[20:21], v[24:25], v[20:21]
	v_pk_add_f32 v[18:19], v[22:23], v[18:19]
	v_mul_f32_e32 v23, v21, v21
	v_mul_f32_e32 v22, v19, v19
	v_fmac_f32_e32 v22, v18, v18
	v_fmac_f32_e32 v23, v20, v20
	v_add_f32_e32 v24, v22, v23
	ds_bpermute_b32 v0, v0, v24
	v_cndmask_b32_e64 v25, v13, v16, s[2:3]
	v_cvt_pk_bf16_f32 v22, v18, v19
	v_cvt_pk_bf16_f32 v23, v20, v21
	s_waitcnt lgkmcnt(0)
	v_add_f32_e32 v18, v24, v0
	v_lshlrev_b32_e32 v0, 2, v25
	ds_bpermute_b32 v19, v0, v18
	v_lshlrev_b32_e32 v0, 11, v17
	v_lshl_add_u64 v[20:21], s[6:7], 0, v[0:1]
	v_lshl_add_u64 v[20:21], v[38:39], 1, v[20:21]
	global_store_dwordx2 v[20:21], v[22:23], off
	s_and_saveexec_b64 s[0:1], vcc
	s_cbranch_execz .LBB0_728
	v_lshlrev_b32_e32 v0, 2, v17
	s_waitcnt lgkmcnt(0)
	v_add_f32_e32 v17, v18, v19
	global_atomic_add_f32 v0, v17, s[10:11]
	s_branch .LBB0_728

; __device__ __forceinline__ unsigned cvt_pk_bf16(float lo, float hi) { const f32v2_t v = {lo, hi}; const bf16v2_t r = __builtin_convertvector(v, bf16v2_t); return __builtin_bit_cast(unsigned, r); }
; __device__ __forceinline__ f32x4 mfma16(const bf16x8& a, const bf16x8& b, const f32x4& c) { return __builtin_amdgcn_mfma_f32_16x16x32_bf16(a, b, c, 0, 0, 0); }
;     __device__ __forceinline__ void operator()(int row, int col, const f32x4& acc) const {
;         if constexpr (NORM) { const f32x4 bv = *(const f32x4*)(base + (size_t)row * DM + col); const f32x4 v = acc + bv;
;             float ss = (v[0] * v[0] + v[1] * v[1]) + (v[2] * v[2] + v[3] * v[3]);
;             u32x2 w; w.x = cvt_pk_bf16(v[0], v[1]); w.y = cvt_pk_bf16(v[2], v[3]); *(u32x2*)(a3 + (size_t)row * DM + col) = w;
;             ss += __shfl_xor(ss, 16); ss += __shfl_xor(ss, 32); if ((threadIdx.x & 48) == 0) atomicAdd(rowss + row, ss);
; template <int KS, class Epi>
; __device__ __forceinline__ void small_gemm(const bf16_t* __restrict__ A, int lda, int a_grp_step, const bf16_t* __restrict__ Bt, int N, const Epi& E, LAS unsigned char* lds) {
;     ...
;         const int tile = pair * 2 + th, tr = tile & 15, tc = tile >> 4, row0 = MP + tr * 32, col0 = tc * 32;
;         const bf16_t* ap = A + (size_t)(row0 + fr) * lda + (col0 >> 8) * a_grp_step + kq * (KS * 32) + 8 * fq;
;         const bf16_t* bp = Bt + (size_t)(col0 + fr) * K + kq * (KS * 32) + 8 * fq;
;         bf16x8 a[KS][2], b[KS][2];
; #pragma unroll
;         for (int k = 0; k < KS; ++k)
; #pragma unroll
;             for (int m = 0; m < 2; ++m) { a[k][m] = *(const bf16x8*)(ap + (size_t)(16 * m) * lda + 32 * k); b[k][m] = *(const bf16x8*)(bp + (size_t)(16 * m) * K + 32 * k); }
;         f32x4 acc[2][2];
; #pragma unroll
;         for (int mi = 0; mi < 2; ++mi)
; #pragma unroll
;             for (int ni = 0; ni < 2; ++ni) acc[mi][ni] = (f32x4){0.f, 0.f, 0.f, 0.f};
; #pragma unroll
;         for (int k = 0; k < KS; ++k)
; #pragma unroll
;             for (int mi = 0; mi < 2; ++mi)
; #pragma unroll
;                 for (int ni = 0; ni < 2; ++ni) acc[mi][ni] = mfma16(b[k][ni], a[k][mi], acc[mi][ni]);
; #pragma unroll
;         for (int mi = 0; mi < 2; ++mi)
; #pragma unroll
;             for (int ni = 0; ni < 2; ++ni) red[(wid * 4 + mi * 2 + ni) * 64 + lane] = acc[mi][ni];
;         lds_barrier();
.LBB0_776:
	v_and_b32_e32 v70, 0xffffffe0, v9
	s_waitcnt lgkmcnt(0)
	v_or_b32_e32 v18, v70, v146
	v_and_b32_e32 v0, 0x1e0, v10
	v_ashrrev_i32_e32 v19, 31, v18
	v_or_b32_e32 v17, 0x4000, v0
	v_lshlrev_b64 v[18:19], 11, v[18:19]
	v_lshl_add_u64 v[62:63], v[4:5], 0, v[18:19]
	v_or_b32_e32 v0, v17, v146
	v_lshlrev_b32_e32 v0, 11, v0
	v_lshl_add_u64 v[64:65], v[2:3], 0, v[0:1]
	v_add_co_u32_e64 v66, s[2:3], s8, v64
	v_addc_co_u32_e64 v67, s[2:3], 0, v65, s[2:3]
	v_add_co_u32_e64 v68, s[2:3], s8, v62
	v_addc_co_u32_e64 v69, s[2:3], 0, v63, s[2:3]
	v_or_b32_e32 v0, v7, v17
	v_cmp_lt_i32_e64 s[2:3], v14, v15
	v_cndmask_b32_e64 v17, v13, v14, s[2:3]
	v_lshlrev_b32_e32 v17, 2, v17
	v_cmp_lt_i32_e64 s[2:3], v16, v15
	v_or_b32_e32 v38, v70, v8
	v_ashrrev_i32_e32 v39, 31, v38
	global_load_dwordx4 v[158:161], v[62:63], off
	global_load_dwordx4 v[162:165], v[64:65], off
	global_load_dwordx4 v[166:169], v[66:67], off
	global_load_dwordx4 v[170:173], v[68:69], off
	global_load_dwordx4 v[174:177], v[62:63], off offset:64
	global_load_dwordx4 v[178:181], v[64:65], off offset:64
	global_load_dwordx4 v[186:189], v[66:67], off offset:64
	global_load_dwordx4 v[190:193], v[68:69], off offset:64
	global_load_dwordx4 v[194:197], v[62:63], off offset:128
	global_load_dwordx4 v[198:201], v[64:65], off offset:128
	global_load_dwordx4 v[202:205], v[66:67], off offset:128
	global_load_dwordx4 v[206:209], v[68:69], off offset:128
	global_load_dwordx4 v[210:213], v[62:63], off offset:192
	global_load_dwordx4 v[214:217], v[64:65], off offset:192
	global_load_dwordx4 v[218:221], v[66:67], off offset:192
	global_load_dwordx4 v[222:225], v[68:69], off offset:192
	global_load_dwordx4 v[226:229], v[62:63], off offset:256
	global_load_dwordx4 v[230:233], v[64:65], off offset:256
	global_load_dwordx4 v[234:237], v[66:67], off offset:256
	global_load_dwordx4 v[238:241], v[68:69], off offset:256
	global_load_dwordx4 v[242:245], v[62:63], off offset:320
	global_load_dwordx4 v[118:121], v[64:65], off offset:320
	global_load_dwordx4 v[122:125], v[66:67], off offset:320
	global_load_dwordx4 v[148:151], v[68:69], off offset:320
	s_waitcnt vmcnt(20)
	v_mfma_f32_16x16x32_bf16 v[18:21], v[158:161], v[162:165], 0
	v_mfma_f32_16x16x32_bf16 v[22:25], v[158:161], v[166:169], 0
	v_mfma_f32_16x16x32_bf16 v[26:29], v[170:173], v[162:165], 0
	v_mfma_f32_16x16x32_bf16 v[30:33], v[170:173], v[166:169], 0
	global_load_dwordx4 v[158:161], v[62:63], off offset:384
	global_load_dwordx4 v[162:165], v[64:65], off offset:384
	global_load_dwordx4 v[166:169], v[66:67], off offset:384
	global_load_dwordx4 v[170:173], v[68:69], off offset:384
	s_waitcnt vmcnt(20)
	v_mfma_f32_16x16x32_bf16 v[18:21], v[174:177], v[178:181], v[18:21]
	v_mfma_f32_16x16x32_bf16 v[22:25], v[174:177], v[186:189], v[22:25]
	v_mfma_f32_16x16x32_bf16 v[26:29], v[190:193], v[178:181], v[26:29]
	v_mfma_f32_16x16x32_bf16 v[30:33], v[190:193], v[186:189], v[30:33]
	global_load_dwordx4 v[174:177], v[62:63], off offset:448
	global_load_dwordx4 v[178:181], v[64:65], off offset:448
	global_load_dwordx4 v[186:189], v[66:67], off offset:448
	global_load_dwordx4 v[190:193], v[68:69], off offset:448
	s_waitcnt vmcnt(20)
	v_mfma_f32_16x16x32_bf16 v[18:21], v[194:197], v[198:201], v[18:21]
	v_mfma_f32_16x16x32_bf16 v[22:25], v[194:197], v[202:205], v[22:25]
	v_mfma_f32_16x16x32_bf16 v[26:29], v[206:209], v[198:201], v[26:29]
	v_mfma_f32_16x16x32_bf16 v[30:33], v[206:209], v[202:205], v[30:33]
	s_waitcnt vmcnt(16)
	v_mfma_f32_16x16x32_bf16 v[18:21], v[210:213], v[214:217], v[18:21]
	v_mfma_f32_16x16x32_bf16 v[22:25], v[210:213], v[218:221], v[22:25]
	v_mfma_f32_16x16x32_bf16 v[26:29], v[222:225], v[214:217], v[26:29]
	v_mfma_f32_16x16x32_bf16 v[30:33], v[222:225], v[218:221], v[30:33]
	s_waitcnt vmcnt(12)
	v_mfma_f32_16x16x32_bf16 v[18:21], v[226:229], v[230:233], v[18:21]
	v_mfma_f32_16x16x32_bf16 v[22:25], v[226:229], v[234:237], v[22:25]
	v_mfma_f32_16x16x32_bf16 v[26:29], v[238:241], v[230:233], v[26:29]
	v_mfma_f32_16x16x32_bf16 v[30:33], v[238:241], v[234:237], v[30:33]
	s_waitcnt vmcnt(8)
	v_mfma_f32_16x16x32_bf16 v[18:21], v[242:245], v[118:121], v[18:21]
	v_mfma_f32_16x16x32_bf16 v[22:25], v[242:245], v[122:125], v[22:25]
	v_mfma_f32_16x16x32_bf16 v[26:29], v[148:151], v[118:121], v[26:29]
	v_mfma_f32_16x16x32_bf16 v[30:33], v[148:151], v[122:125], v[30:33]
	s_waitcnt vmcnt(4)
	v_mfma_f32_16x16x32_bf16 v[18:21], v[158:161], v[162:165], v[18:21]
	v_mfma_f32_16x16x32_bf16 v[22:25], v[158:161], v[166:169], v[22:25]
	v_mfma_f32_16x16x32_bf16 v[26:29], v[170:173], v[162:165], v[26:29]
	v_mfma_f32_16x16x32_bf16 v[30:33], v[170:173], v[166:169], v[30:33]
	s_waitcnt vmcnt(0)
	v_mfma_f32_16x16x32_bf16 v[18:21], v[174:177], v[178:181], v[18:21]
	v_mfma_f32_16x16x32_bf16 v[22:25], v[174:177], v[186:189], v[22:25]
	v_mfma_f32_16x16x32_bf16 v[26:29], v[190:193], v[178:181], v[26:29]
	v_mfma_f32_16x16x32_bf16 v[30:33], v[190:193], v[186:189], v[30:33]
	s_nop 7
	s_nop 3
	ds_write_b128 v11, v[18:21]
	ds_write_b128 v11, v[26:29] offset:1024
	ds_write_b128 v11, v[22:25] offset:2048
	ds_write_b128 v11, v[30:33] offset:3072
	v_lshlrev_b64 v[18:19], 12, v[0:1]
	v_lshl_add_u64 v[18:19], s[4:5], 0, v[18:19]
	s_waitcnt lgkmcnt(0)
	s_barrier
	v_lshl_add_u64 v[18:19], v[38:39], 2, v[18:19]
	global_load_dwordx4 v[18:21], v[18:19], off
	ds_read_b128 v[22:25], v6
	ds_read_b128 v[26:29], v12 offset:4096
	ds_read_b128 v[30:33], v12 offset:8192
	ds_read_b128 v[34:37], v12 offset:12288
	s_waitcnt lgkmcnt(2)
	v_pk_add_f32 v[24:25], v[24:25], v[28:29]
	v_pk_add_f32 v[22:23], v[22:23], v[26:27]
	s_waitcnt lgkmcnt(1)
	v_pk_add_f32 v[24:25], v[24:25], v[32:33]
	v_pk_add_f32 v[22:23], v[22:23], v[30:31]
	s_waitcnt lgkmcnt(0)
	v_pk_add_f32 v[24:25], v[24:25], v[36:37]
	v_pk_add_f32 v[22:23], v[22:23], v[34:35]
	s_waitcnt vmcnt(0)
	v_pk_add_f32 v[20:21], v[24:25], v[20:21]
	v_pk_add_f32 v[18:19], v[22:23], v[18:19]
	v_mul_f32_e32 v23, v21, v21
	v_mul_f32_e32 v22, v19, v19
	v_fmac_f32_e32 v22, v18, v18
	v_fmac_f32_e32 v23, v20, v20
	v_add_f32_e32 v24, v22, v23
	ds_bpermute_b32 v17, v17, v24
	v_cndmask_b32_e64 v25, v13, v16, s[2:3]
	v_cvt_pk_bf16_f32 v22, v18, v19
	v_lshlrev_b32_e32 v18, 2, v25
	v_cvt_pk_bf16_f32 v23, v20, v21
	s_waitcnt lgkmcnt(0)
	v_add_f32_e32 v17, v24, v17
	ds_bpermute_b32 v18, v18, v17
	v_lshlrev_b64 v[20:21], 11, v[0:1]
	v_lshl_add_u64 v[20:21], s[10:11], 0, v[20:21]
	v_lshl_add_u64 v[20:21], v[38:39], 1, v[20:21]
	global_store_dwordx2 v[20:21], v[22:23], off
	s_and_saveexec_b64 s[0:1], vcc
	s_cbranch_execz .LBB0_775
	v_lshl_add_u64 v[20:21], v[0:1], 2, s[12:13]
	s_waitcnt lgkmcnt(0)
	v_add_f32_e32 v0, v17, v18
	global_atomic_add_f32 v[20:21], v0, off
	s_branch .LBB0_775

; __device__ __forceinline__ unsigned cvt_pk_bf16(float lo, float hi) { const f32v2_t v = {lo, hi}; const bf16v2_t r = __builtin_convertvector(v, bf16v2_t); return __builtin_bit_cast(unsigned, r); }
; __device__ __forceinline__ float silu_f(float x) { return x * __builtin_amdgcn_rcpf(1.0f + __expf(-x)); }
; __device__ __forceinline__ f32x4 mfma16(const bf16x8& a, const bf16x8& b, const f32x4& c) { return __builtin_amdgcn_mfma_f32_16x16x32_bf16(a, b, c, 0, 0, 0); }
;     __device__ __forceinline__ void operator()(int row, int col, const f32x4& acc) const {
;         const f32x4 v = acc * rsqrtf(rowss[row] * (1.0f / 1024.0f) + 1e-6f);
;         if (col < 1024) { u32x2 w; w.x = cvt_pk_bf16(v[0], v[1]); w.y = cvt_pk_bf16(v[2], v[3]); *(u32x2*)(U + (size_t)row * DM + col) = w; }
;         else { u32x2 w; w.x = cvt_pk_bf16(silu_f(v[0]), silu_f(v[1])); w.y = cvt_pk_bf16(silu_f(v[2]), silu_f(v[3])); *(u32x2*)(SG + (size_t)row * DM + col - 1024) = w; } }
; template <int KS, class Epi>
; __device__ __forceinline__ void small_gemm(const bf16_t* __restrict__ A, int lda, int a_grp_step, const bf16_t* __restrict__ Bt, int N, const Epi& E, LAS unsigned char* lds) {
;     ...
;         const int tile = pair * 2 + th, tr = tile & 15, tc = tile >> 4, row0 = MP + tr * 32, col0 = tc * 32;
;         const bf16_t* ap = A + (size_t)(row0 + fr) * lda + (col0 >> 8) * a_grp_step + kq * (KS * 32) + 8 * fq;
;         const bf16_t* bp = Bt + (size_t)(col0 + fr) * K + kq * (KS * 32) + 8 * fq;
;         bf16x8 a[KS][2], b[KS][2];
; #pragma unroll
;         for (int k = 0; k < KS; ++k)
; #pragma unroll
;             for (int m = 0; m < 2; ++m) { a[k][m] = *(const bf16x8*)(ap + (size_t)(16 * m) * lda + 32 * k); b[k][m] = *(const bf16x8*)(bp + (size_t)(16 * m) * K + 32 * k); }
;         f32x4 acc[2][2];
; #pragma unroll
;         for (int mi = 0; mi < 2; ++mi)
; #pragma unroll
;             for (int ni = 0; ni < 2; ++ni) acc[mi][ni] = (f32x4){0.f, 0.f, 0.f, 0.f};
; #pragma unroll
;         for (int k = 0; k < KS; ++k)
; #pragma unroll
;             for (int mi = 0; mi < 2; ++mi)
; #pragma unroll
;                 for (int ni = 0; ni < 2; ++ni) acc[mi][ni] = mfma16(b[k][ni], a[k][mi], acc[mi][ni]);
; #pragma unroll
;         for (int mi = 0; mi < 2; ++mi)
; #pragma unroll
;             for (int ni = 0; ni < 2; ++ni) red[(wid * 4 + mi * 2 + ni) * 64 + lane] = acc[mi][ni];
;         lds_barrier();
.LBB0_837:
	v_and_b32_e32 v67, 0xffffffe0, v15
	v_or_b32_e32 v6, v67, v157
	v_and_b32_e32 v0, 0x1e0, v16
	v_ashrrev_i32_e32 v7, 31, v6
	v_or_b32_e32 v66, 0x4000, v0
	v_lshlrev_b64 v[6:7], 11, v[6:7]
	v_lshl_add_u64 v[10:11], v[4:5], 0, v[6:7]
	v_or_b32_e32 v0, v66, v157
	v_lshlrev_b32_e32 v0, 11, v0
	v_lshl_add_u64 v[60:61], v[2:3], 0, v[0:1]
	v_add_co_u32_e32 v62, vcc, s14, v60
	v_addc_co_u32_e32 v63, vcc, 0, v61, vcc
	v_add_co_u32_e32 v64, vcc, s14, v10
	v_addc_co_u32_e32 v65, vcc, 0, v11, vcc
	global_load_dwordx4 v[158:161], v[10:11], off
	global_load_dwordx4 v[162:165], v[60:61], off
	global_load_dwordx4 v[166:169], v[62:63], off
	global_load_dwordx4 v[170:173], v[64:65], off
	global_load_dwordx4 v[174:177], v[10:11], off offset:64
	global_load_dwordx4 v[178:181], v[60:61], off offset:64
	global_load_dwordx4 v[186:189], v[62:63], off offset:64
	global_load_dwordx4 v[190:193], v[64:65], off offset:64
	global_load_dwordx4 v[194:197], v[10:11], off offset:128
	global_load_dwordx4 v[198:201], v[60:61], off offset:128
	global_load_dwordx4 v[202:205], v[62:63], off offset:128
	global_load_dwordx4 v[206:209], v[64:65], off offset:128
	global_load_dwordx4 v[210:213], v[10:11], off offset:192
	global_load_dwordx4 v[214:217], v[60:61], off offset:192
	global_load_dwordx4 v[218:221], v[62:63], off offset:192
	global_load_dwordx4 v[222:225], v[64:65], off offset:192
	global_load_dwordx4 v[226:229], v[10:11], off offset:256
	global_load_dwordx4 v[230:233], v[60:61], off offset:256
	global_load_dwordx4 v[234:237], v[62:63], off offset:256
	global_load_dwordx4 v[238:241], v[64:65], off offset:256
	global_load_dwordx4 v[242:245], v[10:11], off offset:320
	global_load_dwordx4 v[118:121], v[60:61], off offset:320
	global_load_dwordx4 v[122:125], v[62:63], off offset:320
	global_load_dwordx4 v[148:151], v[64:65], off offset:320
	s_waitcnt vmcnt(20)
	v_mfma_f32_16x16x32_bf16 v[6:9], v[158:161], v[162:165], 0
	v_mfma_f32_16x16x32_bf16 v[22:25], v[158:161], v[166:169], 0
	v_mfma_f32_16x16x32_bf16 v[26:29], v[170:173], v[162:165], 0
	v_mfma_f32_16x16x32_bf16 v[30:33], v[170:173], v[166:169], 0
	global_load_dwordx4 v[158:161], v[10:11], off offset:384
	global_load_dwordx4 v[162:165], v[60:61], off offset:384
	global_load_dwordx4 v[166:169], v[62:63], off offset:384
	global_load_dwordx4 v[170:173], v[64:65], off offset:384
	s_waitcnt vmcnt(20)
	v_mfma_f32_16x16x32_bf16 v[6:9], v[174:177], v[178:181], v[6:9]
	v_mfma_f32_16x16x32_bf16 v[22:25], v[174:177], v[186:189], v[22:25]
	v_mfma_f32_16x16x32_bf16 v[26:29], v[190:193], v[178:181], v[26:29]
	v_mfma_f32_16x16x32_bf16 v[30:33], v[190:193], v[186:189], v[30:33]
	global_load_dwordx4 v[174:177], v[10:11], off offset:448
	global_load_dwordx4 v[178:181], v[60:61], off offset:448
	global_load_dwordx4 v[186:189], v[62:63], off offset:448
	global_load_dwordx4 v[190:193], v[64:65], off offset:448
	s_waitcnt vmcnt(20)
	v_mfma_f32_16x16x32_bf16 v[6:9], v[194:197], v[198:201], v[6:9]
	v_mfma_f32_16x16x32_bf16 v[22:25], v[194:197], v[202:205], v[22:25]
	v_mfma_f32_16x16x32_bf16 v[26:29], v[206:209], v[198:201], v[26:29]
	v_mfma_f32_16x16x32_bf16 v[30:33], v[206:209], v[202:205], v[30:33]
	s_waitcnt vmcnt(16)
	v_mfma_f32_16x16x32_bf16 v[6:9], v[210:213], v[214:217], v[6:9]
	v_mfma_f32_16x16x32_bf16 v[22:25], v[210:213], v[218:221], v[22:25]
	v_mfma_f32_16x16x32_bf16 v[26:29], v[222:225], v[214:217], v[26:29]
	v_mfma_f32_16x16x32_bf16 v[30:33], v[222:225], v[218:221], v[30:33]
	s_waitcnt vmcnt(12)
	v_mfma_f32_16x16x32_bf16 v[6:9], v[226:229], v[230:233], v[6:9]
	v_mfma_f32_16x16x32_bf16 v[22:25], v[226:229], v[234:237], v[22:25]
	v_mfma_f32_16x16x32_bf16 v[26:29], v[238:241], v[230:233], v[26:29]
	v_mfma_f32_16x16x32_bf16 v[30:33], v[238:241], v[234:237], v[30:33]
	s_waitcnt vmcnt(8)
	v_mfma_f32_16x16x32_bf16 v[6:9], v[242:245], v[118:121], v[6:9]
	v_mfma_f32_16x16x32_bf16 v[22:25], v[242:245], v[122:125], v[22:25]
	v_mfma_f32_16x16x32_bf16 v[26:29], v[148:151], v[118:121], v[26:29]
	v_mfma_f32_16x16x32_bf16 v[30:33], v[148:151], v[122:125], v[30:33]
	s_waitcnt vmcnt(4)
	v_mfma_f32_16x16x32_bf16 v[6:9], v[158:161], v[162:165], v[6:9]
	v_mfma_f32_16x16x32_bf16 v[22:25], v[158:161], v[166:169], v[22:25]
	v_mfma_f32_16x16x32_bf16 v[26:29], v[170:173], v[162:165], v[26:29]
	v_mfma_f32_16x16x32_bf16 v[30:33], v[170:173], v[166:169], v[30:33]
	s_waitcnt vmcnt(0)
	v_mfma_f32_16x16x32_bf16 v[6:9], v[174:177], v[178:181], v[6:9]
	v_mfma_f32_16x16x32_bf16 v[22:25], v[174:177], v[186:189], v[22:25]
	v_mfma_f32_16x16x32_bf16 v[26:29], v[190:193], v[178:181], v[26:29]
	v_mfma_f32_16x16x32_bf16 v[30:33], v[190:193], v[186:189], v[30:33]
	s_nop 7
	s_nop 3
	ds_write_b128 v17, v[6:9]
	ds_write_b128 v17, v[26:29] offset:1024
	ds_write_b128 v17, v[22:25] offset:2048
	ds_write_b128 v17, v[30:33] offset:3072
	v_or_b32_e32 v7, v13, v66
	s_waitcnt lgkmcnt(0)
	s_barrier
	v_lshlrev_b32_e32 v0, 2, v7
	global_load_dword v0, v0, s[6:7]
	ds_read_b128 v[8:11], v12
	ds_read_b128 v[20:23], v18 offset:4096
	ds_read_b128 v[24:27], v18 offset:8192
	ds_read_b128 v[28:31], v18 offset:12288
	v_or_b32_e32 v6, v67, v14
	v_cmp_lt_i32_e32 vcc, s16, v6
	s_waitcnt lgkmcnt(2)
	v_pk_add_f32 v[8:9], v[8:9], v[20:21]
	v_pk_add_f32 v[10:11], v[10:11], v[22:23]
	s_waitcnt lgkmcnt(1)
	v_pk_add_f32 v[8:9], v[8:9], v[24:25]
	v_pk_add_f32 v[10:11], v[10:11], v[26:27]
	s_waitcnt vmcnt(0)
	v_fmamk_f32 v0, v0, 0x3a800000, v19
	v_mul_f32_e32 v20, 0x4b800000, v0
	v_cmp_gt_f32_e64 s[2:3], s15, v0
	s_waitcnt lgkmcnt(0)
	v_pk_add_f32 v[10:11], v[10:11], v[30:31]
	v_cndmask_b32_e64 v0, v0, v20, s[2:3]
	v_rsq_f32_e32 v0, v0
	v_pk_add_f32 v[20:21], v[8:9], v[28:29]
	v_mul_f32_e32 v8, 0x45800000, v0
	v_cndmask_b32_e64 v0, v0, v8, s[2:3]
	v_pk_mul_f32 v[8:9], v[10:11], v[0:1] op_sel_hi:[1,0]
	v_pk_mul_f32 v[10:11], v[20:21], v[0:1] op_sel_hi:[1,0]
	v_lshlrev_b32_e32 v0, 11, v7
	s_and_saveexec_b64 s[0:1], vcc
	s_xor_b64 s[2:3], exec, s[0:1]
	s_cbranch_execz .LBB0_839
	v_mul_f32_e32 v7, 0xbfb8aa3b, v10
	v_exp_f32_e32 v7, v7
	v_mul_f32_e32 v20, 0xbfb8aa3b, v11
	v_exp_f32_e32 v20, v20
	v_mul_f32_e32 v22, 0xbfb8aa3b, v9
	v_add_f32_e32 v7, 1.0, v7
	v_exp_f32_e32 v23, v22
	v_add_f32_e32 v21, 1.0, v20
	v_rcp_f32_e32 v20, v7
	v_mul_f32_e32 v7, 0xbfb8aa3b, v8
	v_exp_f32_e32 v7, v7
	v_rcp_f32_e32 v21, v21
	v_add_f32_e32 v7, 1.0, v7
	v_rcp_f32_e32 v22, v7
	v_add_f32_e32 v7, 1.0, v23
	v_rcp_f32_e32 v23, v7
	v_pk_mul_f32 v[10:11], v[10:11], v[20:21]
	v_mov_b32_e32 v7, v1
	v_cvt_pk_bf16_f32 v10, v10, v11
	v_pk_mul_f32 v[8:9], v[8:9], v[22:23]
	s_nop 0
	v_cvt_pk_bf16_f32 v11, v8, v9
	v_lshl_add_u64 v[8:9], s[50:51], 0, v[0:1]
	v_lshl_add_u64 v[6:7], v[6:7], 1, v[8:9]
	v_add_co_u32_e32 v6, vcc, 0x71ff000, v6
	s_nop 1
	v_addc_co_u32_e32 v7, vcc, 0, v7, vcc
	global_store_dwordx2 v[6:7], v[10:11], off offset:2048

; __device__ __forceinline__ unsigned cvt_pk_bf16(float lo, float hi) { const f32v2_t v = {lo, hi}; const bf16v2_t r = __builtin_convertvector(v, bf16v2_t); return __builtin_bit_cast(unsigned, r); }
; __device__ __forceinline__ float silu_f(float x) { return x * __builtin_amdgcn_rcpf(1.0f + __expf(-x)); }
; __device__ __forceinline__ f32x4 mfma16(const bf16x8& a, const bf16x8& b, const f32x4& c) { return __builtin_amdgcn_mfma_f32_16x16x32_bf16(a, b, c, 0, 0, 0); }
;     __device__ __forceinline__ void operator()(int row, int col, const f32x4& acc) const {
;         const f32x4 v = acc * rsqrtf(rowss[row] * (1.0f / 1024.0f) + 1e-6f);
;         if (col < 1024) { u32x2 w; w.x = cvt_pk_bf16(v[0], v[1]); w.y = cvt_pk_bf16(v[2], v[3]); *(u32x2*)(U + (size_t)row * DM + col) = w; }
;         else { u32x2 w; w.x = cvt_pk_bf16(silu_f(v[0]), silu_f(v[1])); w.y = cvt_pk_bf16(silu_f(v[2]), silu_f(v[3])); *(u32x2*)(SG + (size_t)row * DM + col - 1024) = w; } }
; template <int KS, class Epi>
; __device__ __forceinline__ void small_gemm(const bf16_t* __restrict__ A, int lda, int a_grp_step, const bf16_t* __restrict__ Bt, int N, const Epi& E, LAS unsigned char* lds) {
;     ...
;         const int tile = pair * 2 + th, tr = tile & 15, tc = tile >> 4, row0 = MP + tr * 32, col0 = tc * 32;
;         const bf16_t* ap = A + (size_t)(row0 + fr) * lda + (col0 >> 8) * a_grp_step + kq * (KS * 32) + 8 * fq;
;         const bf16_t* bp = Bt + (size_t)(col0 + fr) * K + kq * (KS * 32) + 8 * fq;
;         bf16x8 a[KS][2], b[KS][2];
; #pragma unroll
;         for (int k = 0; k < KS; ++k)
; #pragma unroll
;             for (int m = 0; m < 2; ++m) { a[k][m] = *(const bf16x8*)(ap + (size_t)(16 * m) * lda + 32 * k); b[k][m] = *(const bf16x8*)(bp + (size_t)(16 * m) * K + 32 * k); }
;         f32x4 acc[2][2];
; #pragma unroll
;         for (int mi = 0; mi < 2; ++mi)
; #pragma unroll
;             for (int ni = 0; ni < 2; ++ni) acc[mi][ni] = (f32x4){0.f, 0.f, 0.f, 0.f};
; #pragma unroll
;         for (int k = 0; k < KS; ++k)
; #pragma unroll
;             for (int mi = 0; mi < 2; ++mi)
; #pragma unroll
;                 for (int ni = 0; ni < 2; ++ni) acc[mi][ni] = mfma16(b[k][ni], a[k][mi], acc[mi][ni]);
; #pragma unroll
;         for (int mi = 0; mi < 2; ++mi)
; #pragma unroll
;             for (int ni = 0; ni < 2; ++ni) red[(wid * 4 + mi * 2 + ni) * 64 + lane] = acc[mi][ni];
;         lds_barrier();
.LBB0_934:
	v_and_b32_e32 v67, 0xffffffe0, v17
	v_or_b32_e32 v6, v67, v157
	v_and_b32_e32 v0, 0x1e0, v18
	v_ashrrev_i32_e32 v7, 31, v6
	v_or_b32_e32 v66, 0x4000, v0
	v_lshlrev_b64 v[6:7], 11, v[6:7]
	v_lshl_add_u64 v[58:59], v[4:5], 0, v[6:7]
	v_or_b32_e32 v0, v66, v157
	v_lshlrev_b32_e32 v0, 11, v0
	v_lshl_add_u64 v[60:61], v[2:3], 0, v[0:1]
	v_add_co_u32_e32 v62, vcc, s8, v60
	v_addc_co_u32_e32 v63, vcc, 0, v61, vcc
	v_add_co_u32_e32 v64, vcc, s8, v58
	v_addc_co_u32_e32 v65, vcc, 0, v59, vcc
	v_or_b32_e32 v0, v15, v66
	global_load_dwordx4 v[158:161], v[58:59], off
	global_load_dwordx4 v[162:165], v[60:61], off
	global_load_dwordx4 v[166:169], v[62:63], off
	global_load_dwordx4 v[170:173], v[64:65], off
	global_load_dwordx4 v[174:177], v[58:59], off offset:64
	global_load_dwordx4 v[178:181], v[60:61], off offset:64
	global_load_dwordx4 v[186:189], v[62:63], off offset:64
	global_load_dwordx4 v[190:193], v[64:65], off offset:64
	global_load_dwordx4 v[194:197], v[58:59], off offset:128
	global_load_dwordx4 v[198:201], v[60:61], off offset:128
	global_load_dwordx4 v[202:205], v[62:63], off offset:128
	global_load_dwordx4 v[206:209], v[64:65], off offset:128
	global_load_dwordx4 v[210:213], v[58:59], off offset:192
	global_load_dwordx4 v[214:217], v[60:61], off offset:192
	global_load_dwordx4 v[218:221], v[62:63], off offset:192
	global_load_dwordx4 v[222:225], v[64:65], off offset:192
	global_load_dwordx4 v[226:229], v[58:59], off offset:256
	global_load_dwordx4 v[230:233], v[60:61], off offset:256
	global_load_dwordx4 v[234:237], v[62:63], off offset:256
	global_load_dwordx4 v[238:241], v[64:65], off offset:256
	global_load_dwordx4 v[242:245], v[58:59], off offset:320
	global_load_dwordx4 v[118:121], v[60:61], off offset:320
	global_load_dwordx4 v[122:125], v[62:63], off offset:320
	global_load_dwordx4 v[148:151], v[64:65], off offset:320
	s_waitcnt vmcnt(20)
	v_mfma_f32_16x16x32_bf16 v[6:9], v[158:161], v[162:165], 0
	v_mfma_f32_16x16x32_bf16 v[10:13], v[158:161], v[166:169], 0
	v_mfma_f32_16x16x32_bf16 v[22:25], v[170:173], v[162:165], 0
	v_mfma_f32_16x16x32_bf16 v[26:29], v[170:173], v[166:169], 0
	global_load_dwordx4 v[158:161], v[58:59], off offset:384
	global_load_dwordx4 v[162:165], v[60:61], off offset:384
	global_load_dwordx4 v[166:169], v[62:63], off offset:384
	global_load_dwordx4 v[170:173], v[64:65], off offset:384
	s_waitcnt vmcnt(20)
	v_mfma_f32_16x16x32_bf16 v[6:9], v[174:177], v[178:181], v[6:9]
	v_mfma_f32_16x16x32_bf16 v[10:13], v[174:177], v[186:189], v[10:13]
	v_mfma_f32_16x16x32_bf16 v[22:25], v[190:193], v[178:181], v[22:25]
	v_mfma_f32_16x16x32_bf16 v[26:29], v[190:193], v[186:189], v[26:29]
	global_load_dwordx4 v[174:177], v[58:59], off offset:448
	global_load_dwordx4 v[178:181], v[60:61], off offset:448
	global_load_dwordx4 v[186:189], v[62:63], off offset:448
	global_load_dwordx4 v[190:193], v[64:65], off offset:448
	s_waitcnt vmcnt(20)
	v_mfma_f32_16x16x32_bf16 v[6:9], v[194:197], v[198:201], v[6:9]
	v_mfma_f32_16x16x32_bf16 v[10:13], v[194:197], v[202:205], v[10:13]
	v_mfma_f32_16x16x32_bf16 v[22:25], v[206:209], v[198:201], v[22:25]
	v_mfma_f32_16x16x32_bf16 v[26:29], v[206:209], v[202:205], v[26:29]
	s_waitcnt vmcnt(16)
	v_mfma_f32_16x16x32_bf16 v[6:9], v[210:213], v[214:217], v[6:9]
	v_mfma_f32_16x16x32_bf16 v[10:13], v[210:213], v[218:221], v[10:13]
	v_mfma_f32_16x16x32_bf16 v[22:25], v[222:225], v[214:217], v[22:25]
	v_mfma_f32_16x16x32_bf16 v[26:29], v[222:225], v[218:221], v[26:29]
	s_waitcnt vmcnt(12)
	v_mfma_f32_16x16x32_bf16 v[6:9], v[226:229], v[230:233], v[6:9]
	v_mfma_f32_16x16x32_bf16 v[10:13], v[226:229], v[234:237], v[10:13]
	v_mfma_f32_16x16x32_bf16 v[22:25], v[238:241], v[230:233], v[22:25]
	v_mfma_f32_16x16x32_bf16 v[26:29], v[238:241], v[234:237], v[26:29]
	s_waitcnt vmcnt(8)
	v_mfma_f32_16x16x32_bf16 v[6:9], v[242:245], v[118:121], v[6:9]
	v_mfma_f32_16x16x32_bf16 v[10:13], v[242:245], v[122:125], v[10:13]
	v_mfma_f32_16x16x32_bf16 v[22:25], v[148:151], v[118:121], v[22:25]
	v_mfma_f32_16x16x32_bf16 v[26:29], v[148:151], v[122:125], v[26:29]
	s_waitcnt vmcnt(4)
	v_mfma_f32_16x16x32_bf16 v[6:9], v[158:161], v[162:165], v[6:9]
	v_mfma_f32_16x16x32_bf16 v[10:13], v[158:161], v[166:169], v[10:13]
	v_mfma_f32_16x16x32_bf16 v[22:25], v[170:173], v[162:165], v[22:25]
	v_mfma_f32_16x16x32_bf16 v[26:29], v[170:173], v[166:169], v[26:29]
	s_waitcnt vmcnt(0)
	v_mfma_f32_16x16x32_bf16 v[6:9], v[174:177], v[178:181], v[6:9]
	v_mfma_f32_16x16x32_bf16 v[10:13], v[174:177], v[186:189], v[10:13]
	v_mfma_f32_16x16x32_bf16 v[22:25], v[190:193], v[178:181], v[22:25]
	v_mfma_f32_16x16x32_bf16 v[26:29], v[190:193], v[186:189], v[26:29]
	s_nop 7
	s_nop 3
	ds_write_b128 v19, v[6:9]
	ds_write_b128 v19, v[22:25] offset:1024
	ds_write_b128 v19, v[10:13] offset:2048
	ds_write_b128 v19, v[26:29] offset:3072
	s_waitcnt lgkmcnt(0)
	s_barrier
	v_lshl_add_u64 v[6:7], v[0:1], 2, s[14:15]
	global_load_dword v7, v[6:7], off
	ds_read_b128 v[8:11], v14
	ds_read_b128 v[22:25], v20 offset:4096
	ds_read_b128 v[26:29], v20 offset:8192
	ds_read_b128 v[30:33], v20 offset:12288
	v_or_b32_e32 v6, v67, v16
	v_cmp_lt_i32_e32 vcc, s12, v6
	s_waitcnt lgkmcnt(2)
	v_pk_add_f32 v[10:11], v[10:11], v[24:25]
	v_pk_add_f32 v[8:9], v[8:9], v[22:23]
	s_waitcnt lgkmcnt(1)
	v_pk_add_f32 v[10:11], v[10:11], v[28:29]
	v_pk_add_f32 v[8:9], v[8:9], v[26:27]
	s_waitcnt lgkmcnt(0)
	v_pk_add_f32 v[10:11], v[10:11], v[32:33]
	v_pk_add_f32 v[8:9], v[8:9], v[30:31]
	s_waitcnt vmcnt(0)
	v_fmamk_f32 v7, v7, 0x3a800000, v21
	v_mul_f32_e32 v12, 0x4b800000, v7
	v_cmp_gt_f32_e64 s[2:3], s9, v7
	s_nop 1
	v_cndmask_b32_e64 v7, v7, v12, s[2:3]
	v_rsq_f32_e32 v7, v7
	s_nop 0
	v_mul_f32_e32 v12, 0x45800000, v7
	v_cndmask_b32_e64 v12, v7, v12, s[2:3]
	v_pk_mul_f32 v[10:11], v[10:11], v[12:13] op_sel_hi:[1,0]
	v_pk_mul_f32 v[12:13], v[8:9], v[12:13] op_sel_hi:[1,0]
	v_lshlrev_b64 v[8:9], 11, v[0:1]
	s_and_saveexec_b64 s[0:1], vcc
	s_xor_b64 s[0:1], exec, s[0:1]
	s_cbranch_execz .LBB0_936
	v_mul_f32_e32 v0, 0xbfb8aa3b, v12
	v_exp_f32_e32 v0, v0
	v_mul_f32_e32 v7, 0xbfb8aa3b, v13
	v_mul_f32_e32 v23, 0xbfb8aa3b, v11
	v_exp_f32_e32 v7, v7
	v_add_f32_e32 v0, 1.0, v0
	v_rcp_f32_e32 v22, v0
	v_mul_f32_e32 v0, 0xbfb8aa3b, v10
	v_exp_f32_e32 v0, v0
	v_exp_f32_e32 v25, v23
	v_add_f32_e32 v7, 1.0, v7
	v_rcp_f32_e32 v23, v7
	v_add_f32_e32 v0, 1.0, v0
	v_rcp_f32_e32 v24, v0
	v_add_f32_e32 v0, 1.0, v25
	v_rcp_f32_e32 v25, v0
	v_lshl_add_u64 v[8:9], s[50:51], 0, v[8:9]
	v_mov_b32_e32 v7, v1
	v_lshl_add_u64 v[6:7], v[6:7], 1, v[8:9]
	v_pk_mul_f32 v[12:13], v[12:13], v[22:23]
	v_pk_mul_f32 v[10:11], v[10:11], v[24:25]
	v_add_co_u32_e32 v6, vcc, 0x71ff000, v6
	v_cvt_pk_bf16_f32 v12, v12, v13
	v_cvt_pk_bf16_f32 v13, v10, v11
	v_addc_co_u32_e32 v7, vcc, 0, v7, vcc
	global_store_dwordx2 v[6:7], v[12:13], off offset:2048

; __device__ __forceinline__ float bf2f(short b) { return __uint_as_float(((unsigned)(unsigned short)b) << 16); }
; __device__ __forceinline__ f32x4 mfma16(const bf16x8& a, const bf16x8& b, const f32x4& c) { return __builtin_amdgcn_mfma_f32_16x16x32_bf16(a, b, c, 0, 0, 0); }
; __device__ __forceinline__ void lds_barrier() { asm volatile("s_waitcnt lgkmcnt(0)" ::: "memory"); __builtin_amdgcn_s_barrier(); asm volatile("" ::: "memory"); }
;     __device__ __forceinline__ void operator()(int row, int col, const f32x4& acc) const {
;     ...
;         } else { const bf16x4 hb = *(const bf16x4*)(a3 + (size_t)row * DM + col);
;             *(f32x4*)(out + (size_t)row * DM + col) = acc + (f32x4){bf2f(hb[0]), bf2f(hb[1]), bf2f(hb[2]), bf2f(hb[3])}; } }
; template <int KS, class Epi>
; __device__ __forceinline__ void small_gemm(const bf16_t* __restrict__ A, int lda, int a_grp_step, const bf16_t* __restrict__ Bt, int N, const Epi& E, LAS unsigned char* lds) {
;     ...
;         const int tile = pair * 2 + th, tr = tile & 15, tc = tile >> 4, row0 = MP + tr * 32, col0 = tc * 32;
;         const bf16_t* ap = A + (size_t)(row0 + fr) * lda + (col0 >> 8) * a_grp_step + kq * (KS * 32) + 8 * fq;
;         const bf16_t* bp = Bt + (size_t)(col0 + fr) * K + kq * (KS * 32) + 8 * fq;
;         bf16x8 a[KS][2], b[KS][2];
; #pragma unroll
;         for (int k = 0; k < KS; ++k)
; #pragma unroll
;             for (int m = 0; m < 2; ++m) { a[k][m] = *(const bf16x8*)(ap + (size_t)(16 * m) * lda + 32 * k); b[k][m] = *(const bf16x8*)(bp + (size_t)(16 * m) * K + 32 * k); }
;         f32x4 acc[2][2];
; #pragma unroll
;         for (int mi = 0; mi < 2; ++mi)
; #pragma unroll
;             for (int ni = 0; ni < 2; ++ni) acc[mi][ni] = (f32x4){0.f, 0.f, 0.f, 0.f};
; #pragma unroll
;         for (int k = 0; k < KS; ++k)
; #pragma unroll
;             for (int mi = 0; mi < 2; ++mi)
; #pragma unroll
;                 for (int ni = 0; ni < 2; ++ni) acc[mi][ni] = mfma16(b[k][ni], a[k][mi], acc[mi][ni]);
; #pragma unroll
;         for (int mi = 0; mi < 2; ++mi)
; #pragma unroll
;             for (int ni = 0; ni < 2; ++ni) red[(wid * 4 + mi * 2 + ni) * 64 + lane] = acc[mi][ni];
;         lds_barrier();
.LBB0_1459:
	v_and_b32_e32 v0, 0x1e0, v11
	v_and_b32_e32 v66, 0xffffffe0, v10
	v_or_b32_e32 v67, 0x4000, v0
	v_or_b32_e32 v14, v66, v146
	v_or_b32_e32 v0, v67, v146
	v_ashrrev_i32_e32 v15, 31, v14
	v_lshlrev_b32_e32 v0, 11, v0
	v_lshlrev_b64 v[14:15], 11, v[14:15]
	v_lshl_add_u64 v[58:59], v[2:3], 0, v[0:1]
	v_lshl_add_u64 v[60:61], v[4:5], 0, v[14:15]
	v_add_co_u32_e32 v62, vcc, s6, v58
	v_addc_co_u32_e32 v63, vcc, 0, v59, vcc
	v_add_co_u32_e32 v64, vcc, s6, v60
	s_add_i32 s7, s7, s86
	v_addc_co_u32_e32 v65, vcc, 0, v61, vcc
	v_add_u32_e32 v10, s4, v10
	s_cmpk_lt_i32 s7, 0x100
	v_add_u32_e32 v11, s5, v11
	v_or_b32_e32 v38, v67, v9
	v_lshlrev_b32_e32 v0, 11, v38
	v_or_b32_e32 v34, v66, v8
	v_ashrrev_i32_e32 v35, 31, v34
	v_lshl_add_u64 v[36:37], s[0:1], 0, v[0:1]
	v_lshl_add_u64 v[36:37], v[34:35], 1, v[36:37]
	v_lshlrev_b32_e32 v0, 12, v38
	global_load_dwordx4 v[158:161], v[60:61], off
	global_load_dwordx4 v[162:165], v[58:59], off
	global_load_dwordx4 v[166:169], v[62:63], off
	global_load_dwordx4 v[170:173], v[64:65], off
	global_load_dwordx4 v[174:177], v[60:61], off offset:64
	global_load_dwordx4 v[178:181], v[58:59], off offset:64
	global_load_dwordx4 v[186:189], v[62:63], off offset:64
	global_load_dwordx4 v[190:193], v[64:65], off offset:64
	global_load_dwordx4 v[194:197], v[60:61], off offset:128
	global_load_dwordx4 v[198:201], v[58:59], off offset:128
	global_load_dwordx4 v[202:205], v[62:63], off offset:128
	global_load_dwordx4 v[206:209], v[64:65], off offset:128
	global_load_dwordx4 v[210:213], v[60:61], off offset:192
	global_load_dwordx4 v[214:217], v[58:59], off offset:192
	global_load_dwordx4 v[218:221], v[62:63], off offset:192
	global_load_dwordx4 v[222:225], v[64:65], off offset:192
	global_load_dwordx4 v[226:229], v[60:61], off offset:256
	global_load_dwordx4 v[230:233], v[58:59], off offset:256
	global_load_dwordx4 v[234:237], v[62:63], off offset:256
	global_load_dwordx4 v[238:241], v[64:65], off offset:256
	global_load_dwordx4 v[242:245], v[60:61], off offset:320
	global_load_dwordx4 v[118:121], v[58:59], off offset:320
	global_load_dwordx4 v[122:125], v[62:63], off offset:320
	global_load_dwordx4 v[148:151], v[64:65], off offset:320
	s_waitcnt vmcnt(20)
	v_mfma_f32_16x16x32_bf16 v[14:17], v[158:161], v[162:165], 0
	v_mfma_f32_16x16x32_bf16 v[18:21], v[158:161], v[166:169], 0
	v_mfma_f32_16x16x32_bf16 v[22:25], v[170:173], v[162:165], 0
	v_mfma_f32_16x16x32_bf16 v[26:29], v[170:173], v[166:169], 0
	global_load_dwordx4 v[158:161], v[60:61], off offset:384
	global_load_dwordx4 v[162:165], v[58:59], off offset:384
	global_load_dwordx4 v[166:169], v[62:63], off offset:384
	global_load_dwordx4 v[170:173], v[64:65], off offset:384
	s_waitcnt vmcnt(20)
	v_mfma_f32_16x16x32_bf16 v[14:17], v[174:177], v[178:181], v[14:17]
	v_mfma_f32_16x16x32_bf16 v[18:21], v[174:177], v[186:189], v[18:21]
	v_mfma_f32_16x16x32_bf16 v[22:25], v[190:193], v[178:181], v[22:25]
	v_mfma_f32_16x16x32_bf16 v[26:29], v[190:193], v[186:189], v[26:29]
	global_load_dwordx4 v[174:177], v[60:61], off offset:448
	global_load_dwordx4 v[178:181], v[58:59], off offset:448
	global_load_dwordx4 v[186:189], v[62:63], off offset:448
	global_load_dwordx4 v[190:193], v[64:65], off offset:448
	s_waitcnt vmcnt(20)
	v_mfma_f32_16x16x32_bf16 v[14:17], v[194:197], v[198:201], v[14:17]
	v_mfma_f32_16x16x32_bf16 v[18:21], v[194:197], v[202:205], v[18:21]
	v_mfma_f32_16x16x32_bf16 v[22:25], v[206:209], v[198:201], v[22:25]
	v_mfma_f32_16x16x32_bf16 v[26:29], v[206:209], v[202:205], v[26:29]
	s_waitcnt vmcnt(16)
	v_mfma_f32_16x16x32_bf16 v[14:17], v[210:213], v[214:217], v[14:17]
	v_mfma_f32_16x16x32_bf16 v[18:21], v[210:213], v[218:221], v[18:21]
	v_mfma_f32_16x16x32_bf16 v[22:25], v[222:225], v[214:217], v[22:25]
	v_mfma_f32_16x16x32_bf16 v[26:29], v[222:225], v[218:221], v[26:29]
	s_waitcnt vmcnt(12)
	v_mfma_f32_16x16x32_bf16 v[14:17], v[226:229], v[230:233], v[14:17]
	v_mfma_f32_16x16x32_bf16 v[18:21], v[226:229], v[234:237], v[18:21]
	v_mfma_f32_16x16x32_bf16 v[22:25], v[238:241], v[230:233], v[22:25]
	v_mfma_f32_16x16x32_bf16 v[26:29], v[238:241], v[234:237], v[26:29]
	s_waitcnt vmcnt(8)
	v_mfma_f32_16x16x32_bf16 v[14:17], v[242:245], v[118:121], v[14:17]
	v_mfma_f32_16x16x32_bf16 v[18:21], v[242:245], v[122:125], v[18:21]
	v_mfma_f32_16x16x32_bf16 v[22:25], v[148:151], v[118:121], v[22:25]
	v_mfma_f32_16x16x32_bf16 v[26:29], v[148:151], v[122:125], v[26:29]
	s_waitcnt vmcnt(4)
	v_mfma_f32_16x16x32_bf16 v[14:17], v[158:161], v[162:165], v[14:17]
	v_mfma_f32_16x16x32_bf16 v[18:21], v[158:161], v[166:169], v[18:21]
	v_mfma_f32_16x16x32_bf16 v[22:25], v[170:173], v[162:165], v[22:25]
	v_mfma_f32_16x16x32_bf16 v[26:29], v[170:173], v[166:169], v[26:29]
	s_waitcnt vmcnt(0)
	v_mfma_f32_16x16x32_bf16 v[14:17], v[174:177], v[178:181], v[14:17]
	v_mfma_f32_16x16x32_bf16 v[18:21], v[174:177], v[186:189], v[18:21]
	v_mfma_f32_16x16x32_bf16 v[22:25], v[190:193], v[178:181], v[22:25]
	v_mfma_f32_16x16x32_bf16 v[26:29], v[190:193], v[186:189], v[26:29]
	s_nop 7
	s_nop 3
	ds_write_b128 v12, v[14:17]
	ds_write_b128 v12, v[22:25] offset:1024
	ds_write_b128 v12, v[18:21] offset:2048
	ds_write_b128 v12, v[26:29] offset:3072
	s_waitcnt lgkmcnt(0)
	s_barrier
	global_load_dwordx2 v[30:31], v[36:37], off
	v_lshl_add_u64 v[14:15], s[48:49], 0, v[0:1]
	v_lshl_add_u64 v[32:33], v[34:35], 2, v[14:15]
	ds_read_b128 v[14:17], v7
	ds_read_b128 v[18:21], v13 offset:4096
	ds_read_b128 v[22:25], v13 offset:8192
	ds_read_b128 v[26:29], v13 offset:12288
	s_waitcnt lgkmcnt(2)
	v_pk_add_f32 v[16:17], v[16:17], v[20:21]
	v_pk_add_f32 v[14:15], v[14:15], v[18:19]
	s_waitcnt lgkmcnt(1)
	v_pk_add_f32 v[16:17], v[16:17], v[24:25]
	v_pk_add_f32 v[14:15], v[14:15], v[22:23]
	s_waitcnt lgkmcnt(0)
	v_pk_add_f32 v[16:17], v[16:17], v[28:29]
	v_pk_add_f32 v[14:15], v[14:15], v[26:27]
	s_waitcnt vmcnt(0)
	v_and_b32_e32 v19, 0xffff0000, v30
	v_lshlrev_b32_e32 v18, 16, v30
	v_and_b32_e32 v21, 0xffff0000, v31
	v_lshlrev_b32_e32 v20, 16, v31
	v_pk_add_f32 v[16:17], v[16:17], v[20:21]
	v_pk_add_f32 v[14:15], v[14:15], v[18:19]
	global_store_dwordx4 v[32:33], v[14:17], off
	s_waitcnt lgkmcnt(0)
	s_barrier
	s_cbranch_scc1 .LBB0_1459

; __device__ __forceinline__ float bf2f(short b) { return __uint_as_float(((unsigned)(unsigned short)b) << 16); }
; __device__ __forceinline__ f32x4 mfma16(const bf16x8& a, const bf16x8& b, const f32x4& c) { return __builtin_amdgcn_mfma_f32_16x16x32_bf16(a, b, c, 0, 0, 0); }
; __device__ __forceinline__ void lds_barrier() { asm volatile("s_waitcnt lgkmcnt(0)" ::: "memory"); __builtin_amdgcn_s_barrier(); asm volatile("" ::: "memory"); }
;     __device__ __forceinline__ void operator()(int row, int col, const f32x4& acc) const {
;     ...
;         } else { const bf16x4 hb = *(const bf16x4*)(a3 + (size_t)row * DM + col);
;             *(f32x4*)(out + (size_t)row * DM + col) = acc + (f32x4){bf2f(hb[0]), bf2f(hb[1]), bf2f(hb[2]), bf2f(hb[3])}; } }
; template <int KS, class Epi>
; __device__ __forceinline__ void small_gemm(const bf16_t* __restrict__ A, int lda, int a_grp_step, const bf16_t* __restrict__ Bt, int N, const Epi& E, LAS unsigned char* lds) {
;     ...
;         const int tile = pair * 2 + th, tr = tile & 15, tc = tile >> 4, row0 = MP + tr * 32, col0 = tc * 32;
;         const bf16_t* ap = A + (size_t)(row0 + fr) * lda + (col0 >> 8) * a_grp_step + kq * (KS * 32) + 8 * fq;
;         const bf16_t* bp = Bt + (size_t)(col0 + fr) * K + kq * (KS * 32) + 8 * fq;
;         bf16x8 a[KS][2], b[KS][2];
; #pragma unroll
;         for (int k = 0; k < KS; ++k)
; #pragma unroll
;             for (int m = 0; m < 2; ++m) { a[k][m] = *(const bf16x8*)(ap + (size_t)(16 * m) * lda + 32 * k); b[k][m] = *(const bf16x8*)(bp + (size_t)(16 * m) * K + 32 * k); }
;         f32x4 acc[2][2];
; #pragma unroll
;         for (int mi = 0; mi < 2; ++mi)
; #pragma unroll
;             for (int ni = 0; ni < 2; ++ni) acc[mi][ni] = (f32x4){0.f, 0.f, 0.f, 0.f};
; #pragma unroll
;         for (int k = 0; k < KS; ++k)
; #pragma unroll
;             for (int mi = 0; mi < 2; ++mi)
; #pragma unroll
;                 for (int ni = 0; ni < 2; ++ni) acc[mi][ni] = mfma16(b[k][ni], a[k][mi], acc[mi][ni]);
; #pragma unroll
;         for (int mi = 0; mi < 2; ++mi)
; #pragma unroll
;             for (int ni = 0; ni < 2; ++ni) red[(wid * 4 + mi * 2 + ni) * 64 + lane] = acc[mi][ni];
;         lds_barrier();
.LBB0_1486:
	v_and_b32_e32 v0, 0x1e0, v10
	v_and_b32_e32 v13, 0xffffffe0, v9
	v_or_b32_e32 v66, 0x4000, v0
	v_or_b32_e32 v14, v13, v146
	v_or_b32_e32 v0, v66, v146
	v_ashrrev_i32_e32 v15, 31, v14
	v_lshlrev_b32_e32 v0, 11, v0
	v_lshlrev_b64 v[14:15], 11, v[14:15]
	v_lshl_add_u64 v[58:59], v[2:3], 0, v[0:1]
	v_lshl_add_u64 v[60:61], v[4:5], 0, v[14:15]
	v_add_co_u32_e32 v62, vcc, s2, v58
	v_addc_co_u32_e32 v63, vcc, 0, v59, vcc
	v_add_co_u32_e32 v64, vcc, s2, v60
	v_or_b32_e32 v0, v66, v8
	v_addc_co_u32_e32 v65, vcc, 0, v61, vcc
	s_add_i32 s33, s33, s86
	v_add_u32_e32 v9, s0, v9
	s_cmpk_lt_i32 s33, 0x100
	v_add_u32_e32 v10, s1, v10
	v_mov_b32_e32 v35, v1
	v_or_b32_e32 v36, v13, v7
	v_lshlrev_b32_e32 v34, 11, v0
	v_ashrrev_i32_e32 v37, 31, v36
	v_lshl_add_u64 v[34:35], s[4:5], 0, v[34:35]
	v_lshl_add_u64 v[34:35], v[36:37], 1, v[34:35]
	v_lshlrev_b32_e32 v0, 10, v0
	global_load_dwordx4 v[158:161], v[60:61], off
	global_load_dwordx4 v[162:165], v[58:59], off
	global_load_dwordx4 v[166:169], v[62:63], off
	global_load_dwordx4 v[170:173], v[64:65], off
	global_load_dwordx4 v[174:177], v[60:61], off offset:64
	global_load_dwordx4 v[178:181], v[58:59], off offset:64
	global_load_dwordx4 v[186:189], v[62:63], off offset:64
	global_load_dwordx4 v[190:193], v[64:65], off offset:64
	global_load_dwordx4 v[194:197], v[60:61], off offset:128
	global_load_dwordx4 v[198:201], v[58:59], off offset:128
	global_load_dwordx4 v[202:205], v[62:63], off offset:128
	global_load_dwordx4 v[206:209], v[64:65], off offset:128
	global_load_dwordx4 v[210:213], v[60:61], off offset:192
	global_load_dwordx4 v[214:217], v[58:59], off offset:192
	global_load_dwordx4 v[218:221], v[62:63], off offset:192
	global_load_dwordx4 v[222:225], v[64:65], off offset:192
	global_load_dwordx4 v[226:229], v[60:61], off offset:256
	global_load_dwordx4 v[230:233], v[58:59], off offset:256
	global_load_dwordx4 v[234:237], v[62:63], off offset:256
	global_load_dwordx4 v[238:241], v[64:65], off offset:256
	global_load_dwordx4 v[242:245], v[60:61], off offset:320
	global_load_dwordx4 v[118:121], v[58:59], off offset:320
	global_load_dwordx4 v[122:125], v[62:63], off offset:320
	global_load_dwordx4 v[148:151], v[64:65], off offset:320
	s_waitcnt vmcnt(20)
	v_mfma_f32_16x16x32_bf16 v[14:17], v[158:161], v[162:165], 0
	v_mfma_f32_16x16x32_bf16 v[18:21], v[158:161], v[166:169], 0
	v_mfma_f32_16x16x32_bf16 v[22:25], v[170:173], v[162:165], 0
	v_mfma_f32_16x16x32_bf16 v[26:29], v[170:173], v[166:169], 0
	global_load_dwordx4 v[158:161], v[60:61], off offset:384
	global_load_dwordx4 v[162:165], v[58:59], off offset:384
	global_load_dwordx4 v[166:169], v[62:63], off offset:384
	global_load_dwordx4 v[170:173], v[64:65], off offset:384
	s_waitcnt vmcnt(20)
	v_mfma_f32_16x16x32_bf16 v[14:17], v[174:177], v[178:181], v[14:17]
	v_mfma_f32_16x16x32_bf16 v[18:21], v[174:177], v[186:189], v[18:21]
	v_mfma_f32_16x16x32_bf16 v[22:25], v[190:193], v[178:181], v[22:25]
	v_mfma_f32_16x16x32_bf16 v[26:29], v[190:193], v[186:189], v[26:29]
	global_load_dwordx4 v[174:177], v[60:61], off offset:448
	global_load_dwordx4 v[178:181], v[58:59], off offset:448
	global_load_dwordx4 v[186:189], v[62:63], off offset:448
	global_load_dwordx4 v[190:193], v[64:65], off offset:448
	s_waitcnt vmcnt(20)
	v_mfma_f32_16x16x32_bf16 v[14:17], v[194:197], v[198:201], v[14:17]
	v_mfma_f32_16x16x32_bf16 v[18:21], v[194:197], v[202:205], v[18:21]
	v_mfma_f32_16x16x32_bf16 v[22:25], v[206:209], v[198:201], v[22:25]
	v_mfma_f32_16x16x32_bf16 v[26:29], v[206:209], v[202:205], v[26:29]
	s_waitcnt vmcnt(16)
	v_mfma_f32_16x16x32_bf16 v[14:17], v[210:213], v[214:217], v[14:17]
	v_mfma_f32_16x16x32_bf16 v[18:21], v[210:213], v[218:221], v[18:21]
	v_mfma_f32_16x16x32_bf16 v[22:25], v[222:225], v[214:217], v[22:25]
	v_mfma_f32_16x16x32_bf16 v[26:29], v[222:225], v[218:221], v[26:29]
	s_waitcnt vmcnt(12)
	v_mfma_f32_16x16x32_bf16 v[14:17], v[226:229], v[230:233], v[14:17]
	v_mfma_f32_16x16x32_bf16 v[18:21], v[226:229], v[234:237], v[18:21]
	v_mfma_f32_16x16x32_bf16 v[22:25], v[238:241], v[230:233], v[22:25]
	v_mfma_f32_16x16x32_bf16 v[26:29], v[238:241], v[234:237], v[26:29]
	s_waitcnt vmcnt(8)
	v_mfma_f32_16x16x32_bf16 v[14:17], v[242:245], v[118:121], v[14:17]
	v_mfma_f32_16x16x32_bf16 v[18:21], v[242:245], v[122:125], v[18:21]
	v_mfma_f32_16x16x32_bf16 v[22:25], v[148:151], v[118:121], v[22:25]
	v_mfma_f32_16x16x32_bf16 v[26:29], v[148:151], v[122:125], v[26:29]
	s_waitcnt vmcnt(4)
	v_mfma_f32_16x16x32_bf16 v[14:17], v[158:161], v[162:165], v[14:17]
	v_mfma_f32_16x16x32_bf16 v[18:21], v[158:161], v[166:169], v[18:21]
	v_mfma_f32_16x16x32_bf16 v[22:25], v[170:173], v[162:165], v[22:25]
	v_mfma_f32_16x16x32_bf16 v[26:29], v[170:173], v[166:169], v[26:29]
	s_waitcnt vmcnt(0)
	v_mfma_f32_16x16x32_bf16 v[14:17], v[174:177], v[178:181], v[14:17]
	v_mfma_f32_16x16x32_bf16 v[18:21], v[174:177], v[186:189], v[18:21]
	v_mfma_f32_16x16x32_bf16 v[22:25], v[190:193], v[178:181], v[22:25]
	v_mfma_f32_16x16x32_bf16 v[26:29], v[190:193], v[186:189], v[26:29]
	s_nop 7
	s_nop 3
	ds_write_b128 v11, v[14:17]
	ds_write_b128 v11, v[22:25] offset:1024
	ds_write_b128 v11, v[18:21] offset:2048
	ds_write_b128 v11, v[26:29] offset:3072
	s_waitcnt lgkmcnt(0)
	s_barrier
	global_load_dwordx2 v[30:31], v[34:35], off
	v_lshl_add_u64 v[14:15], v[0:1], 2, s[48:49]
	v_lshl_add_u64 v[32:33], v[36:37], 2, v[14:15]
	ds_read_b128 v[14:17], v6
	ds_read_b128 v[18:21], v12 offset:4096
	ds_read_b128 v[22:25], v12 offset:8192
	ds_read_b128 v[26:29], v12 offset:12288
	s_waitcnt lgkmcnt(2)
	v_pk_add_f32 v[16:17], v[16:17], v[20:21]
	v_pk_add_f32 v[14:15], v[14:15], v[18:19]
	s_waitcnt lgkmcnt(1)
	v_pk_add_f32 v[16:17], v[16:17], v[24:25]
	v_pk_add_f32 v[14:15], v[14:15], v[22:23]
	s_waitcnt lgkmcnt(0)
	v_pk_add_f32 v[16:17], v[16:17], v[28:29]
	v_pk_add_f32 v[14:15], v[14:15], v[26:27]
	s_waitcnt vmcnt(0)
	v_and_b32_e32 v19, 0xffff0000, v30
	v_lshlrev_b32_e32 v18, 16, v30
	v_and_b32_e32 v21, 0xffff0000, v31
	v_lshlrev_b32_e32 v20, 16, v31
	v_pk_add_f32 v[16:17], v[16:17], v[20:21]
	v_pk_add_f32 v[14:15], v[14:15], v[18:19]
	global_store_dwordx4 v[32:33], v[14:17], off
	s_waitcnt lgkmcnt(0)
	s_barrier
	s_cbranch_scc1 .LBB0_1486
